# MLA attention loops: fragment ds_reads software-pipelined 5 deep into free VGPR pool, counted lgkmcnt; drop redundant vmcnt(0)
# speedup vs baseline: 1.0090x; 1.0024x over previous
.LBB0_352:
	s_mul_i32 s0, s5, 0xa000
	v_add_u32_e32 v185, s0, v176
	v_add_u32_e32 v187, s0, v178
	v_add_u32_e32 v192, s0, v180
	v_add_u32_e32 v193, s0, v182
	ds_read_b128 v[196:199], v185
	ds_read_b128 v[200:203], v187
	ds_read_b128 v[232:235], v185 offset:12288
	ds_read_b128 v[236:239], v187 offset:12288
	ds_read_b128 v[240:243], v192
	s_waitcnt lgkmcnt(4)
	v_mfma_f32_32x32x16_bf16 v[66:81], v[196:199], v[98:101], 0
	ds_read_b128 v[244:247], v192 offset:12288
	s_waitcnt lgkmcnt(4)
	v_mfma_f32_32x32x16_bf16 v[66:81], v[200:203], v[102:105], v[66:81]
	ds_read_b128 v[196:199], v193
	s_waitcnt lgkmcnt(4)
	v_mfma_f32_32x32x16_bf16 v[82:97], v[232:235], v[98:101], 0
	ds_read_b128 v[200:203], v193 offset:12288
	s_waitcnt lgkmcnt(4)
	v_mfma_f32_32x32x16_bf16 v[82:97], v[236:239], v[102:105], v[82:97]
	ds_read_b128 v[232:235], v185 offset:128
	s_waitcnt lgkmcnt(4)
	v_mfma_f32_32x32x16_bf16 v[66:81], v[240:243], v[106:109], v[66:81]
	ds_read_b128 v[236:239], v185 offset:12416
	s_waitcnt lgkmcnt(4)
	v_mfma_f32_32x32x16_bf16 v[82:97], v[244:247], v[106:109], v[82:97]
	ds_read_b128 v[240:243], v187 offset:128
	s_waitcnt lgkmcnt(4)
	v_mfma_f32_32x32x16_bf16 v[66:81], v[196:199], v[110:113], v[66:81]
	ds_read_b128 v[244:247], v187 offset:12416
	s_waitcnt lgkmcnt(4)
	v_mfma_f32_32x32x16_bf16 v[82:97], v[200:203], v[110:113], v[82:97]
	ds_read_b128 v[196:199], v192 offset:128
	s_waitcnt lgkmcnt(4)
	v_mfma_f32_32x32x16_bf16 v[66:81], v[232:235], v[114:117], v[66:81]
	ds_read_b128 v[200:203], v192 offset:12416
	s_waitcnt lgkmcnt(4)
	v_mfma_f32_32x32x16_bf16 v[82:97], v[236:239], v[114:117], v[82:97]
	ds_read_b128 v[232:235], v193 offset:128
	s_waitcnt lgkmcnt(4)
	v_mfma_f32_32x32x16_bf16 v[66:81], v[240:243], v[118:121], v[66:81]
	ds_read_b128 v[236:239], v193 offset:12416
	s_waitcnt lgkmcnt(4)
	v_mfma_f32_32x32x16_bf16 v[82:97], v[244:247], v[118:121], v[82:97]
	ds_read_b128 v[240:243], v185 offset:256
	s_waitcnt lgkmcnt(4)
	v_mfma_f32_32x32x16_bf16 v[66:81], v[196:199], v[122:125], v[66:81]
	ds_read_b128 v[244:247], v185 offset:12544
	s_waitcnt lgkmcnt(4)
	v_mfma_f32_32x32x16_bf16 v[82:97], v[200:203], v[122:125], v[82:97]
	ds_read_b128 v[196:199], v187 offset:256
	s_waitcnt lgkmcnt(4)
	v_mfma_f32_32x32x16_bf16 v[66:81], v[232:235], v[126:129], v[66:81]
	ds_read_b128 v[200:203], v187 offset:12544
	s_waitcnt lgkmcnt(4)
	v_mfma_f32_32x32x16_bf16 v[82:97], v[236:239], v[126:129], v[82:97]
	ds_read_b128 v[232:235], v192 offset:256
	s_waitcnt lgkmcnt(4)
	v_mfma_f32_32x32x16_bf16 v[66:81], v[240:243], v[130:133], v[66:81]
	ds_read_b128 v[236:239], v192 offset:12544
	s_waitcnt lgkmcnt(4)
	v_mfma_f32_32x32x16_bf16 v[82:97], v[244:247], v[130:133], v[82:97]
	ds_read_b128 v[240:243], v193 offset:12544
	s_waitcnt lgkmcnt(4)
	v_mfma_f32_32x32x16_bf16 v[66:81], v[196:199], v[134:137], v[66:81]
	ds_read_b128 v[244:247], v193 offset:256
	s_waitcnt lgkmcnt(4)
	v_mfma_f32_32x32x16_bf16 v[82:97], v[200:203], v[134:137], v[82:97]
	s_waitcnt lgkmcnt(3)
	v_mfma_f32_32x32x16_bf16 v[66:81], v[232:235], v[138:141], v[66:81]
	s_waitcnt lgkmcnt(2)
	v_mfma_f32_32x32x16_bf16 v[82:97], v[236:239], v[138:141], v[82:97]
	s_waitcnt lgkmcnt(1)
	v_mfma_f32_32x32x16_bf16 v[82:97], v[240:243], v[142:145], v[82:97]
	s_waitcnt lgkmcnt(0)
	v_mfma_f32_32x32x16_bf16 v[66:81], v[244:247], v[142:145], v[66:81]
	s_nop 1
	s_nop 8
	v_max_f32_e32 v185, v83, v83
	s_nop 1
	v_max_f32_e32 v187, v67, v67
	v_max_f32_e32 v185, v187, v185
	v_max_f32_e32 v187, v84, v84
	v_max_f32_e32 v188, v68, v68
	v_max_f32_e32 v187, v188, v187
	v_max_f32_e32 v188, v85, v85
	v_max_f32_e32 v189, v69, v69
	v_max3_f32 v185, v66, v82, v185
	v_max_f32_e32 v188, v189, v188
	v_max3_f32 v185, v185, v187, v188
	v_max_f32_e32 v187, v86, v86
	v_max_f32_e32 v188, v70, v70
	v_max_f32_e32 v187, v188, v187
	v_max_f32_e32 v188, v87, v87
	v_max_f32_e32 v189, v71, v71
	v_max_f32_e32 v188, v189, v188
	v_max3_f32 v185, v185, v187, v188
	v_max_f32_e32 v187, v88, v88
	v_max_f32_e32 v188, v72, v72
	v_max_f32_e32 v187, v188, v187
	v_max_f32_e32 v188, v89, v89
	v_max_f32_e32 v189, v73, v73
	v_max_f32_e32 v188, v189, v188
	v_max3_f32 v185, v185, v187, v188
	v_max_f32_e32 v187, v90, v90
	v_max_f32_e32 v188, v74, v74
	v_max_f32_e32 v187, v188, v187
	v_max_f32_e32 v188, v91, v91
	v_max_f32_e32 v189, v75, v75
	v_max_f32_e32 v188, v189, v188
	v_max3_f32 v185, v185, v187, v188
	v_max_f32_e32 v187, v92, v92
	v_max_f32_e32 v188, v76, v76
	v_max_f32_e32 v187, v188, v187
	v_max_f32_e32 v188, v93, v93
	v_max_f32_e32 v189, v77, v77
	v_max_f32_e32 v188, v189, v188
	v_max3_f32 v185, v185, v187, v188
	v_max_f32_e32 v187, v94, v94
	v_max_f32_e32 v188, v78, v78
	v_max_f32_e32 v187, v188, v187
	v_max_f32_e32 v188, v95, v95
	v_max_f32_e32 v189, v79, v79
	v_max_f32_e32 v188, v189, v188
	v_max3_f32 v185, v185, v187, v188
	v_max_f32_e32 v187, v96, v96
	v_max_f32_e32 v188, v80, v80
	v_max_f32_e32 v187, v188, v187
	v_max_f32_e32 v188, v97, v97
	v_max_f32_e32 v189, v81, v81
	v_max_f32_e32 v188, v189, v188
	v_max3_f32 v185, v185, v187, v188
	v_and_b32_e32 v188, 64, v221
	v_xor_b32_e32 v187, 32, v221
	v_add_u32_e32 v188, 64, v188
	v_cmp_lt_i32_e32 vcc, v187, v188
	s_nop 1
	v_cndmask_b32_e32 v187, v221, v187, vcc
	v_lshlrev_b32_e32 v193, 2, v187
	ds_bpermute_b32 v187, v193, v185
	s_waitcnt lgkmcnt(0)
	v_max3_f32 v185, v186, v185, v187
	v_sub_f32_e32 v66, v66, v185
	v_exp_f32_e32 v187, v66
	v_sub_f32_e32 v66, v82, v185
	v_exp_f32_e32 v188, v66
	v_sub_f32_e32 v66, v67, v185
	v_exp_f32_e32 v67, v66
	v_sub_f32_e32 v66, v83, v185
	v_exp_f32_e32 v83, v66
	v_sub_f32_e32 v68, v68, v185
	v_sub_f32_e32 v84, v84, v185
	v_exp_f32_e32 v68, v68
	v_exp_f32_e32 v84, v84
	v_add_f32_e32 v82, v187, v188
	v_sub_f32_e32 v69, v69, v185
	v_sub_f32_e32 v85, v85, v185
	v_sub_f32_e32 v66, v186, v185
	v_add_f32_e32 v82, 0, v82
	v_add_f32_e32 v186, v67, v83
	v_exp_f32_e32 v69, v69
	v_exp_f32_e32 v85, v85
	v_add_f32_e32 v82, v186, v82
	v_add_f32_e32 v186, v68, v84
	v_sub_f32_e32 v70, v70, v185
	v_add_f32_e32 v82, v186, v82
	v_exp_f32_e32 v186, v70
	v_sub_f32_e32 v70, v86, v185
	v_exp_f32_e32 v86, v70
	v_sub_f32_e32 v70, v71, v185
	v_add_f32_e32 v190, v69, v85
	v_exp_f32_e32 v189, v70
	v_sub_f32_e32 v70, v87, v185
	v_sub_f32_e32 v72, v72, v185
	v_exp_f32_e32 v87, v70
	v_add_f32_e32 v70, v190, v82
	v_exp_f32_e32 v190, v72
	v_sub_f32_e32 v72, v88, v185
	v_exp_f32_e32 v88, v72
	v_add_f32_e32 v71, v186, v86
	v_add_f32_e32 v70, v71, v70
	v_add_f32_e32 v71, v189, v87
	v_sub_f32_e32 v72, v73, v185
	v_exp_f32_e32 v73, v72
	v_sub_f32_e32 v72, v89, v185
	v_add_f32_e32 v70, v71, v70
	v_add_f32_e32 v71, v190, v88
	v_exp_f32_e32 v89, v72
	v_add_f32_e32 v82, v71, v70
	v_sub_f32_e32 v70, v74, v185
	v_sub_f32_e32 v71, v90, v185
	v_exp_f32_e32 v70, v70
	v_exp_f32_e32 v71, v71
	v_sub_f32_e32 v72, v75, v185
	v_sub_f32_e32 v74, v91, v185
	v_exp_f32_e32 v72, v72
	v_exp_f32_e32 v75, v74
	v_sub_f32_e32 v76, v76, v185
	v_sub_f32_e32 v90, v92, v185
	v_sub_f32_e32 v78, v78, v185
	v_exp_f32_e32 v76, v76
	v_exp_f32_e32 v90, v90
	v_sub_f32_e32 v77, v77, v185
	v_sub_f32_e32 v91, v93, v185
	v_exp_f32_e32 v92, v78
	v_sub_f32_e32 v78, v94, v185
	v_add_f32_e32 v191, v73, v89
	v_exp_f32_e32 v77, v77
	v_exp_f32_e32 v91, v91
	v_exp_f32_e32 v93, v78
	v_sub_f32_e32 v78, v79, v185
	v_sub_f32_e32 v79, v80, v185
	v_add_f32_e32 v74, v191, v82
	v_add_f32_e32 v82, v70, v71
	v_exp_f32_e32 v94, v78
	v_sub_f32_e32 v78, v95, v185
	v_exp_f32_e32 v191, v79
	v_sub_f32_e32 v79, v96, v185
	v_add_f32_e32 v74, v82, v74
	v_add_f32_e32 v82, v72, v75
	v_exp_f32_e32 v95, v78
	v_exp_f32_e32 v96, v79
	v_sub_f32_e32 v79, v81, v185
	v_add_f32_e32 v74, v82, v74
	v_add_f32_e32 v82, v76, v90
	v_exp_f32_e32 v192, v79
	v_sub_f32_e32 v79, v97, v185
	v_add_f32_e32 v74, v82, v74
	v_add_f32_e32 v82, v77, v91
	v_exp_f32_e32 v97, v79
	v_add_f32_e32 v74, v82, v74
	v_add_f32_e32 v78, v92, v93
	v_add_f32_e32 v74, v78, v74
	v_add_f32_e32 v78, v94, v95
	v_add_f32_e32 v74, v78, v74
	v_add_f32_e32 v78, v191, v96
	v_add_f32_e32 v74, v78, v74
	v_add_f32_e32 v78, v192, v97
	v_add_f32_e32 v74, v78, v74
	v_exp_f32_e32 v66, v66
	ds_bpermute_b32 v78, v193, v74
	v_cmp_neq_f32_e32 vcc, 1.0, v66
	s_cbranch_vccz .LBB0_354
	v_pk_mul_f32 v[64:65], v[64:65], v[66:67] op_sel_hi:[1,0]
	v_pk_mul_f32 v[62:63], v[62:63], v[66:67] op_sel_hi:[1,0]
	v_pk_mul_f32 v[60:61], v[60:61], v[66:67] op_sel_hi:[1,0]
	v_pk_mul_f32 v[58:59], v[58:59], v[66:67] op_sel_hi:[1,0]
	v_pk_mul_f32 v[56:57], v[56:57], v[66:67] op_sel_hi:[1,0]
	v_pk_mul_f32 v[54:55], v[54:55], v[66:67] op_sel_hi:[1,0]
	v_pk_mul_f32 v[52:53], v[52:53], v[66:67] op_sel_hi:[1,0]
	v_pk_mul_f32 v[50:51], v[50:51], v[66:67] op_sel_hi:[1,0]
	v_pk_mul_f32 v[48:49], v[48:49], v[66:67] op_sel_hi:[1,0]
	v_pk_mul_f32 v[46:47], v[46:47], v[66:67] op_sel_hi:[1,0]
	v_pk_mul_f32 v[44:45], v[44:45], v[66:67] op_sel_hi:[1,0]
	v_pk_mul_f32 v[42:43], v[42:43], v[66:67] op_sel_hi:[1,0]
	v_pk_mul_f32 v[40:41], v[40:41], v[66:67] op_sel_hi:[1,0]
	v_pk_mul_f32 v[38:39], v[38:39], v[66:67] op_sel_hi:[1,0]
	v_pk_mul_f32 v[36:37], v[36:37], v[66:67] op_sel_hi:[1,0]
	v_pk_mul_f32 v[34:35], v[34:35], v[66:67] op_sel_hi:[1,0]
	v_pk_mul_f32 v[32:33], v[32:33], v[66:67] op_sel_hi:[1,0]
	v_pk_mul_f32 v[30:31], v[30:31], v[66:67] op_sel_hi:[1,0]
	v_pk_mul_f32 v[28:29], v[28:29], v[66:67] op_sel_hi:[1,0]
	v_pk_mul_f32 v[26:27], v[26:27], v[66:67] op_sel_hi:[1,0]
	v_pk_mul_f32 v[24:25], v[24:25], v[66:67] op_sel_hi:[1,0]
	v_pk_mul_f32 v[22:23], v[22:23], v[66:67] op_sel_hi:[1,0]
	v_pk_mul_f32 v[20:21], v[20:21], v[66:67] op_sel_hi:[1,0]
	v_pk_mul_f32 v[18:19], v[18:19], v[66:67] op_sel_hi:[1,0]
	v_pk_mul_f32 v[16:17], v[16:17], v[66:67] op_sel_hi:[1,0]
	v_pk_mul_f32 v[14:15], v[14:15], v[66:67] op_sel_hi:[1,0]
	v_pk_mul_f32 v[12:13], v[12:13], v[66:67] op_sel_hi:[1,0]
	v_pk_mul_f32 v[10:11], v[10:11], v[66:67] op_sel_hi:[1,0]
	v_pk_mul_f32 v[8:9], v[8:9], v[66:67] op_sel_hi:[1,0]
	v_pk_mul_f32 v[6:7], v[6:7], v[66:67] op_sel_hi:[1,0]
	v_pk_mul_f32 v[4:5], v[4:5], v[66:67] op_sel_hi:[1,0]
	v_pk_mul_f32 v[2:3], v[2:3], v[66:67] op_sel_hi:[1,0]
.LBB0_354:
	v_add_u32_e32 v204, s0, v177
	v_add_u32_e32 v205, s0, v179
	v_add_u32_e32 v248, s0, v181
	v_add_u32_e32 v249, s0, v183
	ds_read_b128 v[196:199], v204 offset:24576
	ds_read_b128 v[200:203], v205 offset:24576
	ds_read_b128 v[232:235], v248 offset:24576
	ds_read_b128 v[236:239], v249 offset:24576
	ds_read_b128 v[240:243], v204 offset:28672
	s_waitcnt lgkmcnt(5)
	v_add_f32_e32 v82, v74, v78
	v_cvt_pk_bf16_f32 v74, v70, v72
	v_cvt_pk_bf16_f32 v70, v188, v83
	v_fmac_f32_e32 v82, v184, v66
	v_cvt_pk_bf16_f32 v66, v71, v75
	v_cvt_pk_bf16_f32 v71, v84, v85
	v_cvt_pk_bf16_f32 v72, v86, v87
	v_cvt_pk_bf16_f32 v78, v187, v67
	v_cvt_pk_bf16_f32 v79, v68, v69
	v_cvt_pk_bf16_f32 v80, v186, v189
	v_cvt_pk_bf16_f32 v81, v190, v73
	v_cvt_pk_bf16_f32 v73, v88, v89
	s_waitcnt lgkmcnt(4)
	v_mfma_f32_32x32x16_bf16 v[50:65], v[196:199], v[78:81], v[50:65]
	ds_read_b128 v[244:247], v205 offset:28672
	v_cvt_pk_bf16_f32 v75, v76, v77
	v_cvt_pk_bf16_f32 v76, v92, v94
	v_cvt_pk_bf16_f32 v77, v191, v192
	v_cvt_pk_bf16_f32 v67, v90, v91
	s_waitcnt lgkmcnt(4)
	v_mfma_f32_32x32x16_bf16 v[50:65], v[200:203], v[74:77], v[50:65]
	ds_read_b128 v[196:199], v248 offset:28672
	v_cvt_pk_bf16_f32 v68, v93, v95
	v_cvt_pk_bf16_f32 v69, v96, v97
	s_add_i32 s13, s13, 1
	s_add_i32 s0, s5, 1
	s_cmp_lg_u32 s5, 2
	s_cselect_b32 s5, s0, 0
	s_waitcnt lgkmcnt(4)
	v_mfma_f32_32x32x16_bf16 v[50:65], v[232:235], v[70:73], v[50:65]
	ds_read_b128 v[200:203], v249 offset:28672
	s_add_i32 s0, s4, 1
	s_cmp_lg_u32 s4, 2
	s_cselect_b32 s4, s0, 0
	s_add_i32 s96, s96, 64
	s_cmp_lg_u32 s13, 4
	s_waitcnt lgkmcnt(4)
	v_mfma_f32_32x32x16_bf16 v[50:65], v[236:239], v[66:69], v[50:65]
	ds_read_b128 v[232:235], v204 offset:32768
	s_waitcnt lgkmcnt(4)
	v_mfma_f32_32x32x16_bf16 v[34:49], v[240:243], v[78:81], v[34:49]
	ds_read_b128 v[236:239], v205 offset:32768
	s_waitcnt lgkmcnt(4)
	v_mfma_f32_32x32x16_bf16 v[34:49], v[244:247], v[74:77], v[34:49]
	ds_read_b128 v[240:243], v248 offset:32768
	s_waitcnt lgkmcnt(4)
	v_mfma_f32_32x32x16_bf16 v[34:49], v[196:199], v[70:73], v[34:49]
	ds_read_b128 v[244:247], v249 offset:32768
	s_waitcnt lgkmcnt(4)
	v_mfma_f32_32x32x16_bf16 v[34:49], v[200:203], v[66:69], v[34:49]
	ds_read_b128 v[196:199], v204 offset:36864
	s_waitcnt lgkmcnt(4)
	v_mfma_f32_32x32x16_bf16 v[18:33], v[232:235], v[78:81], v[18:33]
	ds_read_b128 v[200:203], v205 offset:36864
	s_waitcnt lgkmcnt(4)
	v_mfma_f32_32x32x16_bf16 v[18:33], v[236:239], v[74:77], v[18:33]
	ds_read_b128 v[232:235], v248 offset:36864
	s_waitcnt lgkmcnt(4)
	v_mfma_f32_32x32x16_bf16 v[18:33], v[240:243], v[70:73], v[18:33]
	ds_read_b128 v[236:239], v249 offset:36864
	s_waitcnt lgkmcnt(4)
	v_mfma_f32_32x32x16_bf16 v[18:33], v[244:247], v[66:69], v[18:33]
	s_waitcnt lgkmcnt(3)
	v_mfma_f32_32x32x16_bf16 v[2:17], v[196:199], v[78:81], v[2:17]
	s_waitcnt lgkmcnt(2)
	v_mfma_f32_32x32x16_bf16 v[2:17], v[200:203], v[74:77], v[2:17]
	s_waitcnt lgkmcnt(1)
	v_mfma_f32_32x32x16_bf16 v[2:17], v[232:235], v[70:73], v[2:17]
	s_waitcnt lgkmcnt(0)
	v_mfma_f32_32x32x16_bf16 v[2:17], v[236:239], v[66:69], v[2:17]
	s_cbranch_scc1 .LBB0_346
	v_div_scale_f32 v0, s[0:1], v82, v82, 1.0
	v_rcp_f32_e32 v68, v0
	v_readlane_b32 s36, v253, 33
	v_lshlrev_b64 v[66:67], 12, v[152:153]
	v_readlane_b32 s48, v253, 45
	v_fma_f32 v69, -v0, v68, 1.0
	v_fmac_f32_e32 v68, v69, v68
	v_div_scale_f32 v69, vcc, 1.0, v82, 1.0
	v_mul_f32_e32 v70, v69, v68
	v_fma_f32 v71, -v0, v70, v69
	v_fmac_f32_e32 v70, v71, v68
	v_readlane_b32 s49, v253, 46
	v_fma_f32 v0, -v0, v70, v69
	s_lshl_b32 s96, s8, 8
	v_lshl_add_u64 v[66:67], s[48:49], 0, v[66:67]
	v_div_fmas_f32 v0, v0, v68, v70
	v_lshl_add_u64 v[66:67], v[66:67], 0, s[96:97]
	v_div_fixup_f32 v68, v0, v82, 1.0
	v_lshlrev_b32_e32 v0, 12, v163
	v_lshl_add_u64 v[66:67], v[66:67], 0, v[0:1]
	v_lshlrev_b32_e32 v0, 3, v162
	v_pk_mul_f32 v[50:51], v[68:69], v[50:51] op_sel_hi:[0,1]
	v_pk_mul_f32 v[52:53], v[68:69], v[52:53] op_sel_hi:[0,1]
	v_pk_mul_f32 v[34:35], v[68:69], v[34:35] op_sel_hi:[0,1]
	v_pk_mul_f32 v[36:37], v[68:69], v[36:37] op_sel_hi:[0,1]
	v_pk_mul_f32 v[18:19], v[68:69], v[18:19] op_sel_hi:[0,1]
	v_pk_mul_f32 v[20:21], v[68:69], v[20:21] op_sel_hi:[0,1]
	v_pk_mul_f32 v[2:3], v[68:69], v[2:3] op_sel_hi:[0,1]
	v_pk_mul_f32 v[4:5], v[68:69], v[4:5] op_sel_hi:[0,1]
	v_lshl_add_u64 v[66:67], v[66:67], 0, v[0:1]
	v_cvt_pk_bf16_f32 v50, v50, v51
	v_cvt_pk_bf16_f32 v51, v52, v53
	v_cvt_pk_bf16_f32 v34, v34, v35
	v_cvt_pk_bf16_f32 v35, v36, v37
	v_cvt_pk_bf16_f32 v18, v18, v19
	v_cvt_pk_bf16_f32 v19, v20, v21
	v_cvt_pk_bf16_f32 v2, v2, v3
	v_cvt_pk_bf16_f32 v3, v4, v5
	global_store_dwordx2 v[66:67], v[50:51], off offset:1024
	v_pk_mul_f32 v[50:51], v[68:69], v[54:55] op_sel_hi:[0,1]
	v_pk_mul_f32 v[52:53], v[68:69], v[56:57] op_sel_hi:[0,1]
	global_store_dwordx2 v[66:67], v[34:35], off offset:1088
	v_pk_mul_f32 v[34:35], v[68:69], v[38:39] op_sel_hi:[0,1]
	v_pk_mul_f32 v[36:37], v[68:69], v[40:41] op_sel_hi:[0,1]
	global_store_dwordx2 v[66:67], v[18:19], off offset:1152
	v_pk_mul_f32 v[18:19], v[68:69], v[22:23] op_sel_hi:[0,1]
	v_pk_mul_f32 v[20:21], v[68:69], v[24:25] op_sel_hi:[0,1]
	global_store_dwordx2 v[66:67], v[2:3], off offset:1216
	v_pk_mul_f32 v[2:3], v[68:69], v[6:7] op_sel_hi:[0,1]
	v_pk_mul_f32 v[4:5], v[68:69], v[8:9] op_sel_hi:[0,1]
	v_cvt_pk_bf16_f32 v50, v50, v51
	v_cvt_pk_bf16_f32 v51, v52, v53
	v_cvt_pk_bf16_f32 v34, v34, v35
	v_cvt_pk_bf16_f32 v35, v36, v37
	v_cvt_pk_bf16_f32 v18, v18, v19
	v_cvt_pk_bf16_f32 v19, v20, v21
	v_cvt_pk_bf16_f32 v2, v2, v3
	v_cvt_pk_bf16_f32 v3, v4, v5
	global_store_dwordx2 v[66:67], v[50:51], off offset:1040
	v_pk_mul_f32 v[50:51], v[68:69], v[58:59] op_sel_hi:[0,1]
	v_pk_mul_f32 v[52:53], v[68:69], v[60:61] op_sel_hi:[0,1]
	global_store_dwordx2 v[66:67], v[34:35], off offset:1104
	v_pk_mul_f32 v[34:35], v[68:69], v[42:43] op_sel_hi:[0,1]
	v_pk_mul_f32 v[36:37], v[68:69], v[44:45] op_sel_hi:[0,1]
	global_store_dwordx2 v[66:67], v[18:19], off offset:1168
	v_pk_mul_f32 v[18:19], v[68:69], v[26:27] op_sel_hi:[0,1]
	v_pk_mul_f32 v[20:21], v[68:69], v[28:29] op_sel_hi:[0,1]
	global_store_dwordx2 v[66:67], v[2:3], off offset:1232
	v_pk_mul_f32 v[2:3], v[68:69], v[10:11] op_sel_hi:[0,1]
	v_pk_mul_f32 v[4:5], v[68:69], v[12:13] op_sel_hi:[0,1]
	v_cvt_pk_bf16_f32 v50, v50, v51
	v_cvt_pk_bf16_f32 v51, v52, v53
	v_cvt_pk_bf16_f32 v34, v34, v35
	v_cvt_pk_bf16_f32 v35, v36, v37
	v_cvt_pk_bf16_f32 v18, v18, v19
	v_cvt_pk_bf16_f32 v19, v20, v21
	v_cvt_pk_bf16_f32 v2, v2, v3
	v_cvt_pk_bf16_f32 v3, v4, v5
	global_store_dwordx2 v[66:67], v[50:51], off offset:1056
	v_pk_mul_f32 v[50:51], v[68:69], v[62:63] op_sel_hi:[0,1]
	v_pk_mul_f32 v[52:53], v[68:69], v[64:65] op_sel_hi:[0,1]
	global_store_dwordx2 v[66:67], v[34:35], off offset:1120
	v_pk_mul_f32 v[34:35], v[68:69], v[46:47] op_sel_hi:[0,1]
	v_pk_mul_f32 v[36:37], v[68:69], v[48:49] op_sel_hi:[0,1]
	global_store_dwordx2 v[66:67], v[18:19], off offset:1184
	v_pk_mul_f32 v[18:19], v[68:69], v[30:31] op_sel_hi:[0,1]
	v_pk_mul_f32 v[20:21], v[68:69], v[32:33] op_sel_hi:[0,1]
	global_store_dwordx2 v[66:67], v[2:3], off offset:1248
	v_pk_mul_f32 v[2:3], v[68:69], v[14:15] op_sel_hi:[0,1]
	v_pk_mul_f32 v[4:5], v[68:69], v[16:17] op_sel_hi:[0,1]
	v_cvt_pk_bf16_f32 v50, v50, v51
	v_cvt_pk_bf16_f32 v51, v52, v53
	v_cvt_pk_bf16_f32 v34, v34, v35
	v_cvt_pk_bf16_f32 v35, v36, v37
	v_cvt_pk_bf16_f32 v18, v18, v19
	v_cvt_pk_bf16_f32 v19, v20, v21
	v_cvt_pk_bf16_f32 v2, v2, v3
	v_cvt_pk_bf16_f32 v3, v4, v5
	v_readlane_b32 s96, v254, 51
	v_readlane_b32 s37, v253, 34
	v_readlane_b32 s38, v253, 35
	v_readlane_b32 s39, v253, 36
	v_readlane_b32 s40, v253, 37
	v_readlane_b32 s41, v253, 38
	v_readlane_b32 s42, v253, 39
	v_readlane_b32 s43, v253, 40
	v_readlane_b32 s44, v253, 41
	v_readlane_b32 s45, v253, 42
	v_readlane_b32 s46, v253, 43
	v_readlane_b32 s47, v253, 44
	v_readlane_b32 s50, v253, 47
	v_readlane_b32 s51, v253, 48
	global_store_dwordx2 v[66:67], v[50:51], off offset:1072
	global_store_dwordx2 v[66:67], v[34:35], off offset:1136
	global_store_dwordx2 v[66:67], v[18:19], off offset:1200
	global_store_dwordx2 v[66:67], v[2:3], off offset:1264

.LBB0_518:
	s_mul_i32 s0, s12, 0xa000
	v_add_u32_e32 v187, s0, v178
	v_add_u32_e32 v189, s0, v180
	v_add_u32_e32 v194, s0, v182
	v_add_u32_e32 v195, s0, v184
	ds_read_b128 v[196:199], v187
	ds_read_b128 v[200:203], v189
	ds_read_b128 v[232:235], v187 offset:12288
	ds_read_b128 v[236:239], v189 offset:12288
	ds_read_b128 v[240:243], v194
	s_waitcnt lgkmcnt(4)
	v_mfma_f32_32x32x16_bf16 v[66:81], v[196:199], v[98:101], 0
	ds_read_b128 v[244:247], v194 offset:12288
	s_waitcnt lgkmcnt(4)
	v_mfma_f32_32x32x16_bf16 v[66:81], v[200:203], v[102:105], v[66:81]
	ds_read_b128 v[196:199], v195
	s_waitcnt lgkmcnt(4)
	v_mfma_f32_32x32x16_bf16 v[82:97], v[232:235], v[98:101], 0
	ds_read_b128 v[200:203], v195 offset:12288
	s_waitcnt lgkmcnt(4)
	v_mfma_f32_32x32x16_bf16 v[82:97], v[236:239], v[102:105], v[82:97]
	ds_read_b128 v[232:235], v187 offset:128
	s_waitcnt lgkmcnt(4)
	v_mfma_f32_32x32x16_bf16 v[66:81], v[240:243], v[106:109], v[66:81]
	ds_read_b128 v[236:239], v187 offset:12416
	s_waitcnt lgkmcnt(4)
	v_mfma_f32_32x32x16_bf16 v[82:97], v[244:247], v[106:109], v[82:97]
	ds_read_b128 v[240:243], v189 offset:128
	s_waitcnt lgkmcnt(4)
	v_mfma_f32_32x32x16_bf16 v[66:81], v[196:199], v[110:113], v[66:81]
	ds_read_b128 v[244:247], v189 offset:12416
	s_waitcnt lgkmcnt(4)
	v_mfma_f32_32x32x16_bf16 v[82:97], v[200:203], v[110:113], v[82:97]
	ds_read_b128 v[196:199], v194 offset:128
	s_waitcnt lgkmcnt(4)
	v_mfma_f32_32x32x16_bf16 v[66:81], v[232:235], v[114:117], v[66:81]
	ds_read_b128 v[200:203], v194 offset:12416
	s_waitcnt lgkmcnt(4)
	v_mfma_f32_32x32x16_bf16 v[82:97], v[236:239], v[114:117], v[82:97]
	ds_read_b128 v[232:235], v195 offset:128
	s_waitcnt lgkmcnt(4)
	v_mfma_f32_32x32x16_bf16 v[66:81], v[240:243], v[118:121], v[66:81]
	ds_read_b128 v[236:239], v195 offset:12416
	s_waitcnt lgkmcnt(4)
	v_mfma_f32_32x32x16_bf16 v[82:97], v[244:247], v[118:121], v[82:97]
	ds_read_b128 v[240:243], v187 offset:256
	s_waitcnt lgkmcnt(4)
	v_mfma_f32_32x32x16_bf16 v[66:81], v[196:199], v[122:125], v[66:81]
	ds_read_b128 v[244:247], v187 offset:12544
	s_waitcnt lgkmcnt(4)
	v_mfma_f32_32x32x16_bf16 v[82:97], v[200:203], v[122:125], v[82:97]
	ds_read_b128 v[196:199], v189 offset:256
	s_waitcnt lgkmcnt(4)
	v_mfma_f32_32x32x16_bf16 v[66:81], v[232:235], v[126:129], v[66:81]
	ds_read_b128 v[200:203], v189 offset:12544
	s_waitcnt lgkmcnt(4)
	v_mfma_f32_32x32x16_bf16 v[82:97], v[236:239], v[126:129], v[82:97]
	ds_read_b128 v[232:235], v194 offset:256
	s_waitcnt lgkmcnt(4)
	v_mfma_f32_32x32x16_bf16 v[66:81], v[240:243], v[130:133], v[66:81]
	ds_read_b128 v[236:239], v194 offset:12544
	s_waitcnt lgkmcnt(4)
	v_mfma_f32_32x32x16_bf16 v[82:97], v[244:247], v[130:133], v[82:97]
	ds_read_b128 v[240:243], v195 offset:12544
	s_waitcnt lgkmcnt(4)
	v_mfma_f32_32x32x16_bf16 v[66:81], v[196:199], v[134:137], v[66:81]
	ds_read_b128 v[244:247], v195 offset:256
	s_waitcnt lgkmcnt(4)
	v_mfma_f32_32x32x16_bf16 v[82:97], v[200:203], v[134:137], v[82:97]
	s_waitcnt lgkmcnt(3)
	v_mfma_f32_32x32x16_bf16 v[66:81], v[232:235], v[138:141], v[66:81]
	s_waitcnt lgkmcnt(2)
	v_mfma_f32_32x32x16_bf16 v[82:97], v[236:239], v[138:141], v[82:97]
	s_waitcnt lgkmcnt(1)
	v_mfma_f32_32x32x16_bf16 v[82:97], v[240:243], v[142:145], v[82:97]
	s_waitcnt lgkmcnt(0)
	v_mfma_f32_32x32x16_bf16 v[66:81], v[244:247], v[142:145], v[66:81]
	s_nop 1
	s_nop 8
	v_max_f32_e32 v187, v83, v83
	s_nop 1
	v_max_f32_e32 v189, v67, v67
	v_max_f32_e32 v187, v189, v187
	v_max_f32_e32 v189, v84, v84
	v_max_f32_e32 v190, v68, v68
	v_max_f32_e32 v189, v190, v189
	v_max_f32_e32 v190, v85, v85
	v_max_f32_e32 v191, v69, v69
	v_max3_f32 v187, v66, v82, v187
	v_max_f32_e32 v190, v191, v190
	v_max3_f32 v187, v187, v189, v190
	v_max_f32_e32 v189, v86, v86
	v_max_f32_e32 v190, v70, v70
	v_max_f32_e32 v189, v190, v189
	v_max_f32_e32 v190, v87, v87
	v_max_f32_e32 v191, v71, v71
	v_max_f32_e32 v190, v191, v190
	v_max3_f32 v187, v187, v189, v190
	v_max_f32_e32 v189, v88, v88
	v_max_f32_e32 v190, v72, v72
	v_max_f32_e32 v189, v190, v189
	v_max_f32_e32 v190, v89, v89
	v_max_f32_e32 v191, v73, v73
	v_max_f32_e32 v190, v191, v190
	v_max3_f32 v187, v187, v189, v190
	v_max_f32_e32 v189, v90, v90
	v_max_f32_e32 v190, v74, v74
	v_max_f32_e32 v189, v190, v189
	v_max_f32_e32 v190, v91, v91
	v_max_f32_e32 v191, v75, v75
	v_max_f32_e32 v190, v191, v190
	v_max3_f32 v187, v187, v189, v190
	v_max_f32_e32 v189, v92, v92
	v_max_f32_e32 v190, v76, v76
	v_max_f32_e32 v189, v190, v189
	v_max_f32_e32 v190, v93, v93
	v_max_f32_e32 v191, v77, v77
	v_max_f32_e32 v190, v191, v190
	v_max3_f32 v187, v187, v189, v190
	v_max_f32_e32 v189, v94, v94
	v_max_f32_e32 v190, v78, v78
	v_max_f32_e32 v189, v190, v189
	v_max_f32_e32 v190, v95, v95
	v_max_f32_e32 v191, v79, v79
	v_max_f32_e32 v190, v191, v190
	v_max3_f32 v187, v187, v189, v190
	v_max_f32_e32 v189, v96, v96
	v_max_f32_e32 v190, v80, v80
	v_max_f32_e32 v189, v190, v189
	v_max_f32_e32 v190, v97, v97
	v_max_f32_e32 v191, v81, v81
	v_max_f32_e32 v190, v191, v190
	v_max3_f32 v187, v187, v189, v190
	v_and_b32_e32 v190, 64, v221
	v_xor_b32_e32 v189, 32, v221
	v_add_u32_e32 v190, 64, v190
	v_cmp_lt_i32_e32 vcc, v189, v190
	s_nop 1
	v_cndmask_b32_e32 v189, v221, v189, vcc
	v_lshlrev_b32_e32 v195, 2, v189
	ds_bpermute_b32 v189, v195, v187
	s_waitcnt lgkmcnt(0)
	v_max3_f32 v187, v188, v187, v189
	v_sub_f32_e32 v66, v66, v187
	v_exp_f32_e32 v189, v66
	v_sub_f32_e32 v66, v82, v187
	v_exp_f32_e32 v190, v66
	v_sub_f32_e32 v66, v67, v187
	v_exp_f32_e32 v67, v66
	v_sub_f32_e32 v66, v83, v187
	v_exp_f32_e32 v83, v66
	v_sub_f32_e32 v68, v68, v187
	v_sub_f32_e32 v84, v84, v187
	v_exp_f32_e32 v68, v68
	v_exp_f32_e32 v84, v84
	v_add_f32_e32 v82, v189, v190
	v_sub_f32_e32 v69, v69, v187
	v_sub_f32_e32 v85, v85, v187
	v_sub_f32_e32 v66, v188, v187
	v_add_f32_e32 v82, 0, v82
	v_add_f32_e32 v188, v67, v83
	v_exp_f32_e32 v69, v69
	v_exp_f32_e32 v85, v85
	v_add_f32_e32 v82, v188, v82
	v_add_f32_e32 v188, v68, v84
	v_sub_f32_e32 v70, v70, v187
	v_add_f32_e32 v82, v188, v82
	v_exp_f32_e32 v188, v70
	v_sub_f32_e32 v70, v86, v187
	v_exp_f32_e32 v86, v70
	v_sub_f32_e32 v70, v71, v187
	v_add_f32_e32 v192, v69, v85
	v_exp_f32_e32 v191, v70
	v_sub_f32_e32 v70, v87, v187
	v_sub_f32_e32 v72, v72, v187
	v_exp_f32_e32 v87, v70
	v_add_f32_e32 v70, v192, v82
	v_exp_f32_e32 v192, v72
	v_sub_f32_e32 v72, v88, v187
	v_exp_f32_e32 v88, v72
	v_add_f32_e32 v71, v188, v86
	v_add_f32_e32 v70, v71, v70
	v_add_f32_e32 v71, v191, v87
	v_sub_f32_e32 v72, v73, v187
	v_exp_f32_e32 v73, v72
	v_sub_f32_e32 v72, v89, v187
	v_add_f32_e32 v70, v71, v70
	v_add_f32_e32 v71, v192, v88
	v_exp_f32_e32 v89, v72
	v_add_f32_e32 v82, v71, v70
	v_sub_f32_e32 v70, v74, v187
	v_sub_f32_e32 v71, v90, v187
	v_exp_f32_e32 v70, v70
	v_exp_f32_e32 v71, v71
	v_sub_f32_e32 v72, v75, v187
	v_sub_f32_e32 v74, v91, v187
	v_exp_f32_e32 v72, v72
	v_exp_f32_e32 v75, v74
	v_sub_f32_e32 v76, v76, v187
	v_sub_f32_e32 v90, v92, v187
	v_sub_f32_e32 v78, v78, v187
	v_exp_f32_e32 v76, v76
	v_exp_f32_e32 v90, v90
	v_sub_f32_e32 v77, v77, v187
	v_sub_f32_e32 v91, v93, v187
	v_exp_f32_e32 v92, v78
	v_sub_f32_e32 v78, v94, v187
	v_add_f32_e32 v193, v73, v89
	v_exp_f32_e32 v77, v77
	v_exp_f32_e32 v91, v91
	v_exp_f32_e32 v93, v78
	v_sub_f32_e32 v78, v79, v187
	v_sub_f32_e32 v79, v80, v187
	v_add_f32_e32 v74, v193, v82
	v_add_f32_e32 v82, v70, v71
	v_exp_f32_e32 v94, v78
	v_sub_f32_e32 v78, v95, v187
	v_exp_f32_e32 v193, v79
	v_sub_f32_e32 v79, v96, v187
	v_add_f32_e32 v74, v82, v74
	v_add_f32_e32 v82, v72, v75
	v_exp_f32_e32 v95, v78
	v_exp_f32_e32 v96, v79
	v_sub_f32_e32 v79, v81, v187
	v_add_f32_e32 v74, v82, v74
	v_add_f32_e32 v82, v76, v90
	v_exp_f32_e32 v194, v79
	v_sub_f32_e32 v79, v97, v187
	v_add_f32_e32 v74, v82, v74
	v_add_f32_e32 v82, v77, v91
	v_exp_f32_e32 v97, v79
	v_add_f32_e32 v74, v82, v74
	v_add_f32_e32 v78, v92, v93
	v_add_f32_e32 v74, v78, v74
	v_add_f32_e32 v78, v94, v95
	v_add_f32_e32 v74, v78, v74
	v_add_f32_e32 v78, v193, v96
	v_add_f32_e32 v74, v78, v74
	v_add_f32_e32 v78, v194, v97
	v_add_f32_e32 v74, v78, v74
	v_exp_f32_e32 v66, v66
	ds_bpermute_b32 v78, v195, v74
	v_cmp_neq_f32_e32 vcc, 1.0, v66
	s_cbranch_vccz .LBB0_520
	v_pk_mul_f32 v[64:65], v[64:65], v[66:67] op_sel_hi:[1,0]
	v_pk_mul_f32 v[62:63], v[62:63], v[66:67] op_sel_hi:[1,0]
	v_pk_mul_f32 v[60:61], v[60:61], v[66:67] op_sel_hi:[1,0]
	v_pk_mul_f32 v[58:59], v[58:59], v[66:67] op_sel_hi:[1,0]
	v_pk_mul_f32 v[56:57], v[56:57], v[66:67] op_sel_hi:[1,0]
	v_pk_mul_f32 v[54:55], v[54:55], v[66:67] op_sel_hi:[1,0]
	v_pk_mul_f32 v[52:53], v[52:53], v[66:67] op_sel_hi:[1,0]
	v_pk_mul_f32 v[50:51], v[50:51], v[66:67] op_sel_hi:[1,0]
	v_pk_mul_f32 v[48:49], v[48:49], v[66:67] op_sel_hi:[1,0]
	v_pk_mul_f32 v[46:47], v[46:47], v[66:67] op_sel_hi:[1,0]
	v_pk_mul_f32 v[44:45], v[44:45], v[66:67] op_sel_hi:[1,0]
	v_pk_mul_f32 v[42:43], v[42:43], v[66:67] op_sel_hi:[1,0]
	v_pk_mul_f32 v[40:41], v[40:41], v[66:67] op_sel_hi:[1,0]
	v_pk_mul_f32 v[38:39], v[38:39], v[66:67] op_sel_hi:[1,0]
	v_pk_mul_f32 v[36:37], v[36:37], v[66:67] op_sel_hi:[1,0]
	v_pk_mul_f32 v[34:35], v[34:35], v[66:67] op_sel_hi:[1,0]
	v_pk_mul_f32 v[32:33], v[32:33], v[66:67] op_sel_hi:[1,0]
	v_pk_mul_f32 v[30:31], v[30:31], v[66:67] op_sel_hi:[1,0]
	v_pk_mul_f32 v[28:29], v[28:29], v[66:67] op_sel_hi:[1,0]
	v_pk_mul_f32 v[26:27], v[26:27], v[66:67] op_sel_hi:[1,0]
	v_pk_mul_f32 v[24:25], v[24:25], v[66:67] op_sel_hi:[1,0]
	v_pk_mul_f32 v[22:23], v[22:23], v[66:67] op_sel_hi:[1,0]
	v_pk_mul_f32 v[20:21], v[20:21], v[66:67] op_sel_hi:[1,0]
	v_pk_mul_f32 v[18:19], v[18:19], v[66:67] op_sel_hi:[1,0]
	v_pk_mul_f32 v[16:17], v[16:17], v[66:67] op_sel_hi:[1,0]
	v_pk_mul_f32 v[14:15], v[14:15], v[66:67] op_sel_hi:[1,0]
	v_pk_mul_f32 v[12:13], v[12:13], v[66:67] op_sel_hi:[1,0]
	v_pk_mul_f32 v[10:11], v[10:11], v[66:67] op_sel_hi:[1,0]
	v_pk_mul_f32 v[8:9], v[8:9], v[66:67] op_sel_hi:[1,0]
	v_pk_mul_f32 v[6:7], v[6:7], v[66:67] op_sel_hi:[1,0]
	v_pk_mul_f32 v[4:5], v[4:5], v[66:67] op_sel_hi:[1,0]
	v_pk_mul_f32 v[2:3], v[2:3], v[66:67] op_sel_hi:[1,0]
.LBB0_520:
	v_add_u32_e32 v204, s0, v179
	v_add_u32_e32 v205, s0, v181
	v_add_u32_e32 v248, s0, v183
	v_add_u32_e32 v249, s0, v185
	ds_read_b128 v[196:199], v204 offset:24576
	ds_read_b128 v[200:203], v205 offset:24576
	ds_read_b128 v[232:235], v248 offset:24576
	ds_read_b128 v[236:239], v249 offset:24576
	ds_read_b128 v[240:243], v204 offset:28672
	s_waitcnt lgkmcnt(5)
	v_add_f32_e32 v82, v74, v78
	v_cvt_pk_bf16_f32 v74, v70, v72
	v_cvt_pk_bf16_f32 v70, v190, v83
	v_fmac_f32_e32 v82, v186, v66
	v_cvt_pk_bf16_f32 v66, v71, v75
	v_cvt_pk_bf16_f32 v71, v84, v85
	v_cvt_pk_bf16_f32 v72, v86, v87
	v_cvt_pk_bf16_f32 v78, v189, v67
	v_cvt_pk_bf16_f32 v79, v68, v69
	v_cvt_pk_bf16_f32 v80, v188, v191
	v_cvt_pk_bf16_f32 v81, v192, v73
	v_cvt_pk_bf16_f32 v73, v88, v89
	s_waitcnt lgkmcnt(4)
	v_mfma_f32_32x32x16_bf16 v[50:65], v[196:199], v[78:81], v[50:65]
	ds_read_b128 v[244:247], v205 offset:28672
	v_cvt_pk_bf16_f32 v75, v76, v77
	v_cvt_pk_bf16_f32 v76, v92, v94
	v_cvt_pk_bf16_f32 v77, v193, v194
	v_cvt_pk_bf16_f32 v67, v90, v91
	s_waitcnt lgkmcnt(4)
	v_mfma_f32_32x32x16_bf16 v[50:65], v[200:203], v[74:77], v[50:65]
	ds_read_b128 v[196:199], v248 offset:28672
	v_cvt_pk_bf16_f32 v68, v93, v95
	v_cvt_pk_bf16_f32 v69, v96, v97
	s_add_i32 s0, s12, 1
	s_cmp_lg_u32 s12, 2
	s_cselect_b32 s12, s0, 0
	s_add_i32 s0, s13, 1
	s_waitcnt lgkmcnt(4)
	v_mfma_f32_32x32x16_bf16 v[50:65], v[232:235], v[70:73], v[50:65]
	ds_read_b128 v[200:203], v249 offset:28672
	s_cmp_lg_u32 s13, 2
	s_cselect_b32 s13, s0, 0
	s_add_i32 s11, s11, 1
	s_cmp_lg_u32 s11, 42
	s_waitcnt lgkmcnt(4)
	v_mfma_f32_32x32x16_bf16 v[50:65], v[236:239], v[66:69], v[50:65]
	ds_read_b128 v[232:235], v204 offset:32768
	s_waitcnt lgkmcnt(4)
	v_mfma_f32_32x32x16_bf16 v[34:49], v[240:243], v[78:81], v[34:49]
	ds_read_b128 v[236:239], v205 offset:32768
	s_waitcnt lgkmcnt(4)
	v_mfma_f32_32x32x16_bf16 v[34:49], v[244:247], v[74:77], v[34:49]
	ds_read_b128 v[240:243], v248 offset:32768
	s_waitcnt lgkmcnt(4)
	v_mfma_f32_32x32x16_bf16 v[34:49], v[196:199], v[70:73], v[34:49]
	ds_read_b128 v[244:247], v249 offset:32768
	s_waitcnt lgkmcnt(4)
	v_mfma_f32_32x32x16_bf16 v[34:49], v[200:203], v[66:69], v[34:49]
	ds_read_b128 v[196:199], v204 offset:36864
	s_waitcnt lgkmcnt(4)
	v_mfma_f32_32x32x16_bf16 v[18:33], v[232:235], v[78:81], v[18:33]
	ds_read_b128 v[200:203], v205 offset:36864
	s_waitcnt lgkmcnt(4)
	v_mfma_f32_32x32x16_bf16 v[18:33], v[236:239], v[74:77], v[18:33]
	ds_read_b128 v[232:235], v248 offset:36864
	s_waitcnt lgkmcnt(4)
	v_mfma_f32_32x32x16_bf16 v[18:33], v[240:243], v[70:73], v[18:33]
	ds_read_b128 v[236:239], v249 offset:36864
	s_waitcnt lgkmcnt(4)
	v_mfma_f32_32x32x16_bf16 v[18:33], v[244:247], v[66:69], v[18:33]
	s_waitcnt lgkmcnt(3)
	v_mfma_f32_32x32x16_bf16 v[2:17], v[196:199], v[78:81], v[2:17]
	s_waitcnt lgkmcnt(2)
	v_mfma_f32_32x32x16_bf16 v[2:17], v[200:203], v[74:77], v[2:17]
	s_waitcnt lgkmcnt(1)
	v_mfma_f32_32x32x16_bf16 v[2:17], v[232:235], v[70:73], v[2:17]
	s_waitcnt lgkmcnt(0)
	v_mfma_f32_32x32x16_bf16 v[2:17], v[236:239], v[66:69], v[2:17]
	s_cbranch_scc1 .LBB0_512
	v_div_scale_f32 v0, s[0:1], v82, v82, 1.0
	v_rcp_f32_e32 v68, v0
	v_readlane_b32 s36, v253, 33
	v_lshlrev_b64 v[66:67], 12, v[152:153]
	v_readlane_b32 s48, v253, 45
	v_fma_f32 v69, -v0, v68, 1.0
	v_fmac_f32_e32 v68, v69, v68
	v_div_scale_f32 v69, vcc, 1.0, v82, 1.0
	v_mul_f32_e32 v70, v69, v68
	v_fma_f32 v71, -v0, v70, v69
	v_fmac_f32_e32 v70, v71, v68
	v_readlane_b32 s49, v253, 46
	v_fma_f32 v0, -v0, v70, v69
	s_lshl_b32 s96, s10, 8
	v_lshl_add_u64 v[66:67], s[48:49], 0, v[66:67]
	v_div_fmas_f32 v0, v0, v68, v70
	v_lshl_add_u64 v[66:67], v[66:67], 0, s[96:97]
	v_div_fixup_f32 v68, v0, v82, 1.0
	v_lshlrev_b32_e32 v0, 12, v176
	v_lshl_add_u64 v[66:67], v[66:67], 0, v[0:1]
	v_lshlrev_b32_e32 v0, 3, v175
	v_pk_mul_f32 v[50:51], v[68:69], v[50:51] op_sel_hi:[0,1]
	v_pk_mul_f32 v[52:53], v[68:69], v[52:53] op_sel_hi:[0,1]
	v_pk_mul_f32 v[34:35], v[68:69], v[34:35] op_sel_hi:[0,1]
	v_pk_mul_f32 v[36:37], v[68:69], v[36:37] op_sel_hi:[0,1]
	v_pk_mul_f32 v[18:19], v[68:69], v[18:19] op_sel_hi:[0,1]
	v_pk_mul_f32 v[20:21], v[68:69], v[20:21] op_sel_hi:[0,1]
	v_pk_mul_f32 v[2:3], v[68:69], v[2:3] op_sel_hi:[0,1]
	v_pk_mul_f32 v[4:5], v[68:69], v[4:5] op_sel_hi:[0,1]
	v_lshl_add_u64 v[66:67], v[66:67], 0, v[0:1]
	v_cvt_pk_bf16_f32 v50, v50, v51
	v_cvt_pk_bf16_f32 v51, v52, v53
	v_cvt_pk_bf16_f32 v34, v34, v35
	v_cvt_pk_bf16_f32 v35, v36, v37
	v_cvt_pk_bf16_f32 v18, v18, v19
	v_cvt_pk_bf16_f32 v19, v20, v21
	v_cvt_pk_bf16_f32 v2, v2, v3
	v_cvt_pk_bf16_f32 v3, v4, v5
	global_store_dwordx2 v[66:67], v[50:51], off offset:1024
	v_pk_mul_f32 v[50:51], v[68:69], v[54:55] op_sel_hi:[0,1]
	v_pk_mul_f32 v[52:53], v[68:69], v[56:57] op_sel_hi:[0,1]
	global_store_dwordx2 v[66:67], v[34:35], off offset:1088
	v_pk_mul_f32 v[34:35], v[68:69], v[38:39] op_sel_hi:[0,1]
	v_pk_mul_f32 v[36:37], v[68:69], v[40:41] op_sel_hi:[0,1]
	global_store_dwordx2 v[66:67], v[18:19], off offset:1152
	v_pk_mul_f32 v[18:19], v[68:69], v[22:23] op_sel_hi:[0,1]
	v_pk_mul_f32 v[20:21], v[68:69], v[24:25] op_sel_hi:[0,1]
	global_store_dwordx2 v[66:67], v[2:3], off offset:1216
	v_pk_mul_f32 v[2:3], v[68:69], v[6:7] op_sel_hi:[0,1]
	v_pk_mul_f32 v[4:5], v[68:69], v[8:9] op_sel_hi:[0,1]
	v_cvt_pk_bf16_f32 v50, v50, v51
	v_cvt_pk_bf16_f32 v51, v52, v53
	v_cvt_pk_bf16_f32 v34, v34, v35
	v_cvt_pk_bf16_f32 v35, v36, v37
	v_cvt_pk_bf16_f32 v18, v18, v19
	v_cvt_pk_bf16_f32 v19, v20, v21
	v_cvt_pk_bf16_f32 v2, v2, v3
	v_cvt_pk_bf16_f32 v3, v4, v5
	global_store_dwordx2 v[66:67], v[50:51], off offset:1040
	v_pk_mul_f32 v[50:51], v[68:69], v[58:59] op_sel_hi:[0,1]
	v_pk_mul_f32 v[52:53], v[68:69], v[60:61] op_sel_hi:[0,1]
	global_store_dwordx2 v[66:67], v[34:35], off offset:1104
	v_pk_mul_f32 v[34:35], v[68:69], v[42:43] op_sel_hi:[0,1]
	v_pk_mul_f32 v[36:37], v[68:69], v[44:45] op_sel_hi:[0,1]
	global_store_dwordx2 v[66:67], v[18:19], off offset:1168
	v_pk_mul_f32 v[18:19], v[68:69], v[26:27] op_sel_hi:[0,1]
	v_pk_mul_f32 v[20:21], v[68:69], v[28:29] op_sel_hi:[0,1]
	global_store_dwordx2 v[66:67], v[2:3], off offset:1232
	v_pk_mul_f32 v[2:3], v[68:69], v[10:11] op_sel_hi:[0,1]
	v_pk_mul_f32 v[4:5], v[68:69], v[12:13] op_sel_hi:[0,1]
	v_cvt_pk_bf16_f32 v50, v50, v51
	v_cvt_pk_bf16_f32 v51, v52, v53
	v_cvt_pk_bf16_f32 v34, v34, v35
	v_cvt_pk_bf16_f32 v35, v36, v37
	v_cvt_pk_bf16_f32 v18, v18, v19
	v_cvt_pk_bf16_f32 v19, v20, v21
	v_cvt_pk_bf16_f32 v2, v2, v3
	v_cvt_pk_bf16_f32 v3, v4, v5
	global_store_dwordx2 v[66:67], v[50:51], off offset:1056
	v_pk_mul_f32 v[50:51], v[68:69], v[62:63] op_sel_hi:[0,1]
	v_pk_mul_f32 v[52:53], v[68:69], v[64:65] op_sel_hi:[0,1]
	global_store_dwordx2 v[66:67], v[34:35], off offset:1120
	v_pk_mul_f32 v[34:35], v[68:69], v[46:47] op_sel_hi:[0,1]
	v_pk_mul_f32 v[36:37], v[68:69], v[48:49] op_sel_hi:[0,1]
	global_store_dwordx2 v[66:67], v[18:19], off offset:1184
	v_pk_mul_f32 v[18:19], v[68:69], v[30:31] op_sel_hi:[0,1]
	v_pk_mul_f32 v[20:21], v[68:69], v[32:33] op_sel_hi:[0,1]
	global_store_dwordx2 v[66:67], v[2:3], off offset:1248
	v_pk_mul_f32 v[2:3], v[68:69], v[14:15] op_sel_hi:[0,1]
	v_pk_mul_f32 v[4:5], v[68:69], v[16:17] op_sel_hi:[0,1]
	v_cvt_pk_bf16_f32 v50, v50, v51
	v_cvt_pk_bf16_f32 v51, v52, v53
	v_cvt_pk_bf16_f32 v34, v34, v35
	v_cvt_pk_bf16_f32 v35, v36, v37
	v_cvt_pk_bf16_f32 v18, v18, v19
	v_cvt_pk_bf16_f32 v19, v20, v21
	v_cvt_pk_bf16_f32 v2, v2, v3
	v_cvt_pk_bf16_f32 v3, v4, v5
	v_readlane_b32 s96, v254, 51
	v_readlane_b32 s37, v253, 34
	v_readlane_b32 s38, v253, 35
	v_readlane_b32 s39, v253, 36
	v_readlane_b32 s40, v253, 37
	v_readlane_b32 s41, v253, 38
	v_readlane_b32 s42, v253, 39
	v_readlane_b32 s43, v253, 40
	v_readlane_b32 s44, v253, 41
	v_readlane_b32 s45, v253, 42
	v_readlane_b32 s46, v253, 43
	v_readlane_b32 s47, v253, 44
	v_readlane_b32 s50, v253, 47
	v_readlane_b32 s51, v253, 48
	global_store_dwordx2 v[66:67], v[50:51], off offset:1072
	global_store_dwordx2 v[66:67], v[34:35], off offset:1136
	global_store_dwordx2 v[66:67], v[18:19], off offset:1200
	global_store_dwordx2 v[66:67], v[2:3], off offset:1264
